# v50 + lean barrier: acquire invalidate issued by wave 1 right after the arrival s_barrier (off wave 0's atomic/writeback chain; one invalidate per workgroup as before)
# baseline (speedup 1.0000x reference)
.LBB0_233:
	s_cmp_gt_i32 s59, 2
	s_cselect_b64 s[6:7], -1, 0
	s_and_b64 s[0:1], s[0:1], s[6:7]
	s_andn2_b64 vcc, exec, s[0:1]
	s_cbranch_vccnz .LBB0_287
	s_waitcnt vmcnt(0) lgkmcnt(0)
	s_barrier
	s_mov_b64 s[0:1], exec
	v_readlane_b32 s2, v249, 5
	v_readlane_b32 s3, v249, 6
	v_readlane_b32 s8, v249, 4
	s_and_b64 s[2:3], s[0:1], s[2:3]
	s_mov_b64 exec, s[2:3]
	s_cbranch_execz .Lgb_1_sib
	v_mov_b32_e32 v1, 0x27e00
	ds_read2_b32 v[2:3], v1 offset1:1
	s_lshl_b32 s8, s8, 8
	s_add_u32 s4, s56, s8
	s_addc_u32 s5, s57, 0
	v_mov_b32_e32 v4, 0x1000
	v_mov_b32_e32 v5, 1
	global_atomic_add v6, v4, v5, s[4:5] offset:1024 sc0
	s_waitcnt lgkmcnt(0)
	v_mul_lo_u32 v7, v2, 2
	s_waitcnt vmcnt(0)
	v_add_u32_e32 v6, 1, v6
	v_cmp_eq_u32_e32 vcc, v6, v7
	s_cbranch_vccz .Lgb_1_wait
	buffer_wbl2 sc1
	s_waitcnt vmcnt(0)
	v_mov_b32_e32 v4, 0x3000
	global_atomic_add v8, v4, v5, s[56:57] offset:1024 sc0
	v_mul_lo_u32 v7, v3, 2
	s_waitcnt vmcnt(0)
	v_add_u32_e32 v8, 1, v8
	v_cmp_eq_u32_e32 vcc, v8, v7
	s_cbranch_vccz .Lgb_1_wait
	v_mov_b32_e32 v9, 0x2400
	global_atomic_add v9, v5, s[56:57] offset:0
	global_atomic_add v9, v5, s[56:57] offset:256
	global_atomic_add v9, v5, s[56:57] offset:512
	global_atomic_add v9, v5, s[56:57] offset:768
	global_atomic_add v9, v5, s[56:57] offset:1024
	global_atomic_add v9, v5, s[56:57] offset:1280
	global_atomic_add v9, v5, s[56:57] offset:1536
	global_atomic_add v9, v5, s[56:57] offset:1792
	global_atomic_add v9, v5, s[56:57] offset:2048
	global_atomic_add v9, v5, s[56:57] offset:2304
	global_atomic_add v9, v5, s[56:57] offset:2560
	global_atomic_add v9, v5, s[56:57] offset:2816
	global_atomic_add v9, v5, s[56:57] offset:3072
	global_atomic_add v9, v5, s[56:57] offset:3328
	global_atomic_add v9, v5, s[56:57] offset:3584
	global_atomic_add v9, v5, s[56:57] offset:3840
	s_waitcnt vmcnt(0)
	s_branch .Lgb_1_done

.Lgb_1_spin:
	global_load_dword v8, v9, s[4:5] offset:1024 sc1
	s_waitcnt vmcnt(0)
	v_cmp_ne_u32_e32 vcc, 1, v8
	s_cbranch_vccnz .Lgb_1_done
	s_sleep 1
	s_add_u32 s8, s8, 1
	s_cmp_lt_u32 s8, 0x40000
	s_cbranch_scc1 .Lgb_1_spin
	s_branch .Lgb_1_done
.Lgb_1_sib:
	v_readlane_b32 s8, v249, 7
	s_mov_b64 exec, s[0:1]
	s_cmp_lg_u32 s8, 64
	s_cbranch_scc1 .Lgb_1_done
	buffer_inv sc1

.LBB0_320:
	s_cmp_gt_i32 s59, 3
	s_cselect_b64 s[6:7], -1, 0
	s_and_b64 s[2:3], s[4:5], s[6:7]
	s_andn2_b64 vcc, exec, s[2:3]
	s_cbranch_vccnz .LBB0_374
	s_waitcnt vmcnt(0) lgkmcnt(0)
	s_barrier
	s_mov_b64 s[2:3], exec
	v_readlane_b32 s4, v249, 5
	v_readlane_b32 s5, v249, 6
	v_readlane_b32 s10, v249, 4
	s_and_b64 s[4:5], s[2:3], s[4:5]
	s_mov_b64 exec, s[4:5]
	s_cbranch_execz .Lgb_2_sib
	v_mov_b32_e32 v1, 0x27e00
	ds_read2_b32 v[2:3], v1 offset1:1
	s_lshl_b32 s10, s10, 8
	s_add_u32 s8, s56, s10
	s_addc_u32 s9, s57, 0
	v_mov_b32_e32 v4, 0x1000
	v_mov_b32_e32 v5, 1
	global_atomic_add v6, v4, v5, s[8:9] offset:1024 sc0
	s_waitcnt lgkmcnt(0)
	v_mul_lo_u32 v7, v2, 3
	s_waitcnt vmcnt(0)
	v_add_u32_e32 v6, 1, v6
	v_cmp_eq_u32_e32 vcc, v6, v7
	s_cbranch_vccz .Lgb_2_wait
	buffer_wbl2 sc1
	s_waitcnt vmcnt(0)
	v_mov_b32_e32 v4, 0x3000
	global_atomic_add v8, v4, v5, s[56:57] offset:1024 sc0
	v_mul_lo_u32 v7, v3, 3
	s_waitcnt vmcnt(0)
	v_add_u32_e32 v8, 1, v8
	v_cmp_eq_u32_e32 vcc, v8, v7
	s_cbranch_vccz .Lgb_2_wait
	v_mov_b32_e32 v9, 0x2400
	global_atomic_add v9, v5, s[56:57] offset:0
	global_atomic_add v9, v5, s[56:57] offset:256
	global_atomic_add v9, v5, s[56:57] offset:512
	global_atomic_add v9, v5, s[56:57] offset:768
	global_atomic_add v9, v5, s[56:57] offset:1024
	global_atomic_add v9, v5, s[56:57] offset:1280
	global_atomic_add v9, v5, s[56:57] offset:1536
	global_atomic_add v9, v5, s[56:57] offset:1792
	global_atomic_add v9, v5, s[56:57] offset:2048
	global_atomic_add v9, v5, s[56:57] offset:2304
	global_atomic_add v9, v5, s[56:57] offset:2560
	global_atomic_add v9, v5, s[56:57] offset:2816
	global_atomic_add v9, v5, s[56:57] offset:3072
	global_atomic_add v9, v5, s[56:57] offset:3328
	global_atomic_add v9, v5, s[56:57] offset:3584
	global_atomic_add v9, v5, s[56:57] offset:3840
	s_waitcnt vmcnt(0)
	s_branch .Lgb_2_done

.Lgb_2_spin:
	global_load_dword v8, v9, s[8:9] offset:1024 sc1
	s_waitcnt vmcnt(0)
	v_cmp_ne_u32_e32 vcc, 2, v8
	s_cbranch_vccnz .Lgb_2_done
	s_sleep 1
	s_add_u32 s10, s10, 1
	s_cmp_lt_u32 s10, 0x40000
	s_cbranch_scc1 .Lgb_2_spin
	s_branch .Lgb_2_done
.Lgb_2_sib:
	v_readlane_b32 s10, v249, 7
	s_mov_b64 exec, s[2:3]
	s_cmp_lg_u32 s10, 64
	s_cbranch_scc1 .Lgb_2_done
	buffer_inv sc1

.LBB0_413:
	s_cmp_gt_i32 s59, 4
	s_cselect_b64 s[6:7], -1, 0
	s_and_b64 s[2:3], s[4:5], s[6:7]
	s_andn2_b64 vcc, exec, s[2:3]
	s_cbranch_vccnz .LBB0_467
	s_waitcnt vmcnt(0) lgkmcnt(0)
	s_barrier
	s_mov_b64 s[2:3], exec
	v_readlane_b32 s4, v249, 5
	v_readlane_b32 s5, v249, 6
	v_readlane_b32 s10, v249, 4
	s_and_b64 s[4:5], s[2:3], s[4:5]
	s_mov_b64 exec, s[4:5]
	s_cbranch_execz .Lgb_3_sib
	v_mov_b32_e32 v1, 0x27e00
	ds_read2_b32 v[2:3], v1 offset1:1
	s_lshl_b32 s10, s10, 8
	s_add_u32 s8, s56, s10
	s_addc_u32 s9, s57, 0
	v_mov_b32_e32 v4, 0x1000
	v_mov_b32_e32 v5, 1
	global_atomic_add v6, v4, v5, s[8:9] offset:1024 sc0
	s_waitcnt lgkmcnt(0)
	v_mul_lo_u32 v7, v2, 4
	s_waitcnt vmcnt(0)
	v_add_u32_e32 v6, 1, v6
	v_cmp_eq_u32_e32 vcc, v6, v7
	s_cbranch_vccz .Lgb_3_wait
	buffer_wbl2 sc1
	s_waitcnt vmcnt(0)
	v_mov_b32_e32 v4, 0x3000
	global_atomic_add v8, v4, v5, s[56:57] offset:1024 sc0
	v_mul_lo_u32 v7, v3, 4
	s_waitcnt vmcnt(0)
	v_add_u32_e32 v8, 1, v8
	v_cmp_eq_u32_e32 vcc, v8, v7
	s_cbranch_vccz .Lgb_3_wait
	v_mov_b32_e32 v9, 0x2400
	global_atomic_add v9, v5, s[56:57] offset:0
	global_atomic_add v9, v5, s[56:57] offset:256
	global_atomic_add v9, v5, s[56:57] offset:512
	global_atomic_add v9, v5, s[56:57] offset:768
	global_atomic_add v9, v5, s[56:57] offset:1024
	global_atomic_add v9, v5, s[56:57] offset:1280
	global_atomic_add v9, v5, s[56:57] offset:1536
	global_atomic_add v9, v5, s[56:57] offset:1792
	global_atomic_add v9, v5, s[56:57] offset:2048
	global_atomic_add v9, v5, s[56:57] offset:2304
	global_atomic_add v9, v5, s[56:57] offset:2560
	global_atomic_add v9, v5, s[56:57] offset:2816
	global_atomic_add v9, v5, s[56:57] offset:3072
	global_atomic_add v9, v5, s[56:57] offset:3328
	global_atomic_add v9, v5, s[56:57] offset:3584
	global_atomic_add v9, v5, s[56:57] offset:3840
	s_waitcnt vmcnt(0)
	s_branch .Lgb_3_done

.Lgb_3_spin:
	global_load_dword v8, v9, s[8:9] offset:1024 sc1
	s_waitcnt vmcnt(0)
	v_cmp_ne_u32_e32 vcc, 3, v8
	s_cbranch_vccnz .Lgb_3_done
	s_sleep 1
	s_add_u32 s10, s10, 1
	s_cmp_lt_u32 s10, 0x40000
	s_cbranch_scc1 .Lgb_3_spin
	s_branch .Lgb_3_done

.LBB0_484:
	s_cmp_gt_i32 s59, 5
	s_cselect_b64 s[6:7], -1, 0
	s_and_b64 s[2:3], s[4:5], s[6:7]
	s_andn2_b64 vcc, exec, s[2:3]
	s_cbranch_vccnz .LBB0_538
	s_waitcnt vmcnt(0) lgkmcnt(0)
	s_barrier
	s_mov_b64 s[2:3], exec
	v_readlane_b32 s4, v249, 5
	v_readlane_b32 s5, v249, 6
	v_readlane_b32 s10, v249, 4
	s_and_b64 s[4:5], s[2:3], s[4:5]
	s_mov_b64 exec, s[4:5]
	s_cbranch_execz .Lgb_4_sib
	v_mov_b32_e32 v1, 0x27e00
	ds_read2_b32 v[2:3], v1 offset1:1
	s_lshl_b32 s10, s10, 8
	s_add_u32 s8, s56, s10
	s_addc_u32 s9, s57, 0
	v_mov_b32_e32 v4, 0x1000
	v_mov_b32_e32 v5, 1
	global_atomic_add v6, v4, v5, s[8:9] offset:1024 sc0
	s_waitcnt lgkmcnt(0)
	v_mul_lo_u32 v7, v2, 5
	s_waitcnt vmcnt(0)
	v_add_u32_e32 v6, 1, v6
	v_cmp_eq_u32_e32 vcc, v6, v7
	s_cbranch_vccz .Lgb_4_wait
	buffer_wbl2 sc1
	s_waitcnt vmcnt(0)
	v_mov_b32_e32 v4, 0x3000
	global_atomic_add v8, v4, v5, s[56:57] offset:1024 sc0
	v_mul_lo_u32 v7, v3, 5
	s_waitcnt vmcnt(0)
	v_add_u32_e32 v8, 1, v8
	v_cmp_eq_u32_e32 vcc, v8, v7
	s_cbranch_vccz .Lgb_4_wait
	v_mov_b32_e32 v9, 0x2400
	global_atomic_add v9, v5, s[56:57] offset:0
	global_atomic_add v9, v5, s[56:57] offset:256
	global_atomic_add v9, v5, s[56:57] offset:512
	global_atomic_add v9, v5, s[56:57] offset:768
	global_atomic_add v9, v5, s[56:57] offset:1024
	global_atomic_add v9, v5, s[56:57] offset:1280
	global_atomic_add v9, v5, s[56:57] offset:1536
	global_atomic_add v9, v5, s[56:57] offset:1792
	global_atomic_add v9, v5, s[56:57] offset:2048
	global_atomic_add v9, v5, s[56:57] offset:2304
	global_atomic_add v9, v5, s[56:57] offset:2560
	global_atomic_add v9, v5, s[56:57] offset:2816
	global_atomic_add v9, v5, s[56:57] offset:3072
	global_atomic_add v9, v5, s[56:57] offset:3328
	global_atomic_add v9, v5, s[56:57] offset:3584
	global_atomic_add v9, v5, s[56:57] offset:3840
	s_waitcnt vmcnt(0)
	s_branch .Lgb_4_done

.Lgb_4_spin:
	global_load_dword v8, v9, s[8:9] offset:1024 sc1
	s_waitcnt vmcnt(0)
	v_cmp_ne_u32_e32 vcc, 4, v8
	s_cbranch_vccnz .Lgb_4_done
	s_sleep 1
	s_add_u32 s10, s10, 1
	s_cmp_lt_u32 s10, 0x40000
	s_cbranch_scc1 .Lgb_4_spin
	s_branch .Lgb_4_done

.LBB0_681:
	s_cmp_gt_i32 s59, 7
	s_cselect_b64 s[4:5], -1, 0
	s_and_b64 s[2:3], s[10:11], s[4:5]
	s_andn2_b64 vcc, exec, s[2:3]
	s_cbranch_vccnz .LBB0_735
	s_waitcnt vmcnt(0) lgkmcnt(0)
	s_barrier
	s_mov_b64 s[2:3], exec
	v_readlane_b32 s6, v249, 5
	v_readlane_b32 s7, v249, 6
	v_readlane_b32 s10, v249, 4
	s_and_b64 s[6:7], s[2:3], s[6:7]
	s_mov_b64 exec, s[6:7]
	s_cbranch_execz .Lgb_5_sib
	v_mov_b32_e32 v1, 0x27e00
	ds_read2_b32 v[2:3], v1 offset1:1
	s_lshl_b32 s10, s10, 8
	s_add_u32 s8, s56, s10
	s_addc_u32 s9, s57, 0
	v_mov_b32_e32 v4, 0x1000
	v_mov_b32_e32 v5, 1
	global_atomic_add v6, v4, v5, s[8:9] offset:1024 sc0
	s_waitcnt lgkmcnt(0)
	v_mul_lo_u32 v7, v2, 6
	s_waitcnt vmcnt(0)
	v_add_u32_e32 v6, 1, v6
	v_cmp_eq_u32_e32 vcc, v6, v7
	s_cbranch_vccz .Lgb_5_wait
	buffer_wbl2 sc1
	s_waitcnt vmcnt(0)
	v_mov_b32_e32 v4, 0x3000
	global_atomic_add v8, v4, v5, s[56:57] offset:1024 sc0
	v_mul_lo_u32 v7, v3, 6
	s_waitcnt vmcnt(0)
	v_add_u32_e32 v8, 1, v8
	v_cmp_eq_u32_e32 vcc, v8, v7
	s_cbranch_vccz .Lgb_5_wait
	v_mov_b32_e32 v9, 0x2400
	global_atomic_add v9, v5, s[56:57] offset:0
	global_atomic_add v9, v5, s[56:57] offset:256
	global_atomic_add v9, v5, s[56:57] offset:512
	global_atomic_add v9, v5, s[56:57] offset:768
	global_atomic_add v9, v5, s[56:57] offset:1024
	global_atomic_add v9, v5, s[56:57] offset:1280
	global_atomic_add v9, v5, s[56:57] offset:1536
	global_atomic_add v9, v5, s[56:57] offset:1792
	global_atomic_add v9, v5, s[56:57] offset:2048
	global_atomic_add v9, v5, s[56:57] offset:2304
	global_atomic_add v9, v5, s[56:57] offset:2560
	global_atomic_add v9, v5, s[56:57] offset:2816
	global_atomic_add v9, v5, s[56:57] offset:3072
	global_atomic_add v9, v5, s[56:57] offset:3328
	global_atomic_add v9, v5, s[56:57] offset:3584
	global_atomic_add v9, v5, s[56:57] offset:3840
	s_waitcnt vmcnt(0)
	s_branch .Lgb_5_done

.Lgb_5_spin:
	global_load_dword v8, v9, s[8:9] offset:1024 sc1
	s_waitcnt vmcnt(0)
	v_cmp_ne_u32_e32 vcc, 5, v8
	s_cbranch_vccnz .Lgb_5_done
	s_sleep 1
	s_add_u32 s10, s10, 1
	s_cmp_lt_u32 s10, 0x40000
	s_cbranch_scc1 .Lgb_5_spin
	s_branch .Lgb_5_done

.LBB0_752:
	s_cmp_gt_i32 s59, 8
	s_cselect_b64 s[4:5], -1, 0
	s_and_b64 s[2:3], s[6:7], s[4:5]
	s_andn2_b64 vcc, exec, s[2:3]
	s_cbranch_vccnz .LBB0_806
	s_waitcnt vmcnt(0) lgkmcnt(0)
	s_barrier
	s_mov_b64 s[2:3], exec
	v_readlane_b32 s6, v249, 5
	v_readlane_b32 s7, v249, 6
	v_readlane_b32 s10, v249, 4
	s_and_b64 s[6:7], s[2:3], s[6:7]
	s_mov_b64 exec, s[6:7]
	s_cbranch_execz .Lgb_6_sib
	v_mov_b32_e32 v1, 0x27e00
	ds_read2_b32 v[2:3], v1 offset1:1
	s_lshl_b32 s10, s10, 8
	s_add_u32 s8, s56, s10
	s_addc_u32 s9, s57, 0
	v_mov_b32_e32 v4, 0x1000
	v_mov_b32_e32 v5, 1
	global_atomic_add v6, v4, v5, s[8:9] offset:1024 sc0
	s_waitcnt lgkmcnt(0)
	v_mul_lo_u32 v7, v2, 7
	s_waitcnt vmcnt(0)
	v_add_u32_e32 v6, 1, v6
	v_cmp_eq_u32_e32 vcc, v6, v7
	s_cbranch_vccz .Lgb_6_wait
	buffer_wbl2 sc1
	s_waitcnt vmcnt(0)
	v_mov_b32_e32 v4, 0x3000
	global_atomic_add v8, v4, v5, s[56:57] offset:1024 sc0
	v_mul_lo_u32 v7, v3, 7
	s_waitcnt vmcnt(0)
	v_add_u32_e32 v8, 1, v8
	v_cmp_eq_u32_e32 vcc, v8, v7
	s_cbranch_vccz .Lgb_6_wait
	v_mov_b32_e32 v9, 0x2400
	global_atomic_add v9, v5, s[56:57] offset:0
	global_atomic_add v9, v5, s[56:57] offset:256
	global_atomic_add v9, v5, s[56:57] offset:512
	global_atomic_add v9, v5, s[56:57] offset:768
	global_atomic_add v9, v5, s[56:57] offset:1024
	global_atomic_add v9, v5, s[56:57] offset:1280
	global_atomic_add v9, v5, s[56:57] offset:1536
	global_atomic_add v9, v5, s[56:57] offset:1792
	global_atomic_add v9, v5, s[56:57] offset:2048
	global_atomic_add v9, v5, s[56:57] offset:2304
	global_atomic_add v9, v5, s[56:57] offset:2560
	global_atomic_add v9, v5, s[56:57] offset:2816
	global_atomic_add v9, v5, s[56:57] offset:3072
	global_atomic_add v9, v5, s[56:57] offset:3328
	global_atomic_add v9, v5, s[56:57] offset:3584
	global_atomic_add v9, v5, s[56:57] offset:3840
	s_waitcnt vmcnt(0)
	s_branch .Lgb_6_done

.Lgb_6_spin:
	global_load_dword v8, v9, s[8:9] offset:1024 sc1
	s_waitcnt vmcnt(0)
	v_cmp_ne_u32_e32 vcc, 6, v8
	s_cbranch_vccnz .Lgb_6_done
	s_sleep 1
	s_add_u32 s10, s10, 1
	s_cmp_lt_u32 s10, 0x40000
	s_cbranch_scc1 .Lgb_6_spin
	s_branch .Lgb_6_done

.LBB0_949:
	s_cmp_gt_i32 s59, 10
	s_cselect_b64 s[4:5], -1, 0
	s_and_b64 s[0:1], s[10:11], s[4:5]
	s_andn2_b64 vcc, exec, s[0:1]
	s_cbranch_vccnz .LBB0_1003
	s_waitcnt vmcnt(0) lgkmcnt(0)
	s_barrier
	s_mov_b64 s[0:1], exec
	v_readlane_b32 s2, v249, 5
	v_readlane_b32 s3, v249, 6
	v_readlane_b32 s8, v249, 4
	s_and_b64 s[2:3], s[0:1], s[2:3]
	s_mov_b64 exec, s[2:3]
	s_cbranch_execz .Lgb_7_sib
	v_mov_b32_e32 v1, 0x27e00
	ds_read2_b32 v[2:3], v1 offset1:1
	s_lshl_b32 s8, s8, 8
	s_add_u32 s6, s56, s8
	s_addc_u32 s7, s57, 0
	v_mov_b32_e32 v4, 0x1000
	v_mov_b32_e32 v5, 1
	global_atomic_add v6, v4, v5, s[6:7] offset:1024 sc0
	s_waitcnt lgkmcnt(0)
	v_mul_lo_u32 v7, v2, 8
	s_waitcnt vmcnt(0)
	v_add_u32_e32 v6, 1, v6
	v_cmp_eq_u32_e32 vcc, v6, v7
	s_cbranch_vccz .Lgb_7_wait
	buffer_wbl2 sc1
	s_waitcnt vmcnt(0)
	v_mov_b32_e32 v4, 0x3000
	global_atomic_add v8, v4, v5, s[56:57] offset:1024 sc0
	v_mul_lo_u32 v7, v3, 8
	s_waitcnt vmcnt(0)
	v_add_u32_e32 v8, 1, v8
	v_cmp_eq_u32_e32 vcc, v8, v7
	s_cbranch_vccz .Lgb_7_wait
	v_mov_b32_e32 v9, 0x2400
	global_atomic_add v9, v5, s[56:57] offset:0
	global_atomic_add v9, v5, s[56:57] offset:256
	global_atomic_add v9, v5, s[56:57] offset:512
	global_atomic_add v9, v5, s[56:57] offset:768
	global_atomic_add v9, v5, s[56:57] offset:1024
	global_atomic_add v9, v5, s[56:57] offset:1280
	global_atomic_add v9, v5, s[56:57] offset:1536
	global_atomic_add v9, v5, s[56:57] offset:1792
	global_atomic_add v9, v5, s[56:57] offset:2048
	global_atomic_add v9, v5, s[56:57] offset:2304
	global_atomic_add v9, v5, s[56:57] offset:2560
	global_atomic_add v9, v5, s[56:57] offset:2816
	global_atomic_add v9, v5, s[56:57] offset:3072
	global_atomic_add v9, v5, s[56:57] offset:3328
	global_atomic_add v9, v5, s[56:57] offset:3584
	global_atomic_add v9, v5, s[56:57] offset:3840
	s_waitcnt vmcnt(0)
	s_branch .Lgb_7_done

.Lgb_7_spin:
	global_load_dword v8, v9, s[6:7] offset:1024 sc1
	s_waitcnt vmcnt(0)
	v_cmp_ne_u32_e32 vcc, 7, v8
	s_cbranch_vccnz .Lgb_7_done
	s_sleep 1
	s_add_u32 s8, s8, 1
	s_cmp_lt_u32 s8, 0x40000
	s_cbranch_scc1 .Lgb_7_spin
	s_branch .Lgb_7_done

.LBB0_1041:
	s_cmp_gt_i32 s59, 11
	s_cselect_b64 s[4:5], -1, 0
	s_and_b64 s[0:1], s[0:1], s[4:5]
	s_andn2_b64 vcc, exec, s[0:1]
	s_cbranch_vccnz .LBB0_1095
	s_waitcnt vmcnt(0) lgkmcnt(0)
	s_barrier
	s_mov_b64 s[0:1], exec
	v_readlane_b32 s2, v249, 5
	v_readlane_b32 s3, v249, 6
	v_readlane_b32 s8, v249, 4
	s_and_b64 s[2:3], s[0:1], s[2:3]
	s_mov_b64 exec, s[2:3]
	s_cbranch_execz .Lgb_8_sib
	v_mov_b32_e32 v1, 0x27e00
	ds_read2_b32 v[2:3], v1 offset1:1
	s_lshl_b32 s8, s8, 8
	s_add_u32 s6, s56, s8
	s_addc_u32 s7, s57, 0
	v_mov_b32_e32 v4, 0x1000
	v_mov_b32_e32 v5, 1
	global_atomic_add v6, v4, v5, s[6:7] offset:1024 sc0
	s_waitcnt lgkmcnt(0)
	v_mul_lo_u32 v7, v2, 9
	s_waitcnt vmcnt(0)
	v_add_u32_e32 v6, 1, v6
	v_cmp_eq_u32_e32 vcc, v6, v7
	s_cbranch_vccz .Lgb_8_wait
	buffer_wbl2 sc1
	s_waitcnt vmcnt(0)
	v_mov_b32_e32 v4, 0x3000
	global_atomic_add v8, v4, v5, s[56:57] offset:1024 sc0
	v_mul_lo_u32 v7, v3, 9
	s_waitcnt vmcnt(0)
	v_add_u32_e32 v8, 1, v8
	v_cmp_eq_u32_e32 vcc, v8, v7
	s_cbranch_vccz .Lgb_8_wait
	v_mov_b32_e32 v9, 0x2400
	global_atomic_add v9, v5, s[56:57] offset:0
	global_atomic_add v9, v5, s[56:57] offset:256
	global_atomic_add v9, v5, s[56:57] offset:512
	global_atomic_add v9, v5, s[56:57] offset:768
	global_atomic_add v9, v5, s[56:57] offset:1024
	global_atomic_add v9, v5, s[56:57] offset:1280
	global_atomic_add v9, v5, s[56:57] offset:1536
	global_atomic_add v9, v5, s[56:57] offset:1792
	global_atomic_add v9, v5, s[56:57] offset:2048
	global_atomic_add v9, v5, s[56:57] offset:2304
	global_atomic_add v9, v5, s[56:57] offset:2560
	global_atomic_add v9, v5, s[56:57] offset:2816
	global_atomic_add v9, v5, s[56:57] offset:3072
	global_atomic_add v9, v5, s[56:57] offset:3328
	global_atomic_add v9, v5, s[56:57] offset:3584
	global_atomic_add v9, v5, s[56:57] offset:3840
	s_waitcnt vmcnt(0)
	s_branch .Lgb_8_done

.Lgb_8_spin:
	global_load_dword v8, v9, s[6:7] offset:1024 sc1
	s_waitcnt vmcnt(0)
	v_cmp_ne_u32_e32 vcc, 8, v8
	s_cbranch_vccnz .Lgb_8_done
	s_sleep 1
	s_add_u32 s8, s8, 1
	s_cmp_lt_u32 s8, 0x40000
	s_cbranch_scc1 .Lgb_8_spin
	s_branch .Lgb_8_done

.LBB0_1214:
	s_cmp_gt_i32 s59, 12
	s_cselect_b64 s[4:5], -1, 0
	s_and_b64 s[6:7], s[36:37], s[4:5]
	s_andn2_b64 vcc, exec, s[6:7]
	s_cbranch_vccnz .LBB0_1268
	s_waitcnt vmcnt(0) lgkmcnt(0)
	s_barrier
	s_mov_b64 s[6:7], exec
	v_readlane_b32 s8, v249, 5
	v_readlane_b32 s9, v249, 6
	v_readlane_b32 s12, v249, 4
	s_and_b64 s[8:9], s[6:7], s[8:9]
	s_mov_b64 exec, s[8:9]
	s_cbranch_execz .Lgb_9_sib
	v_mov_b32_e32 v1, 0x27e00
	ds_read2_b32 v[2:3], v1 offset1:1
	s_lshl_b32 s12, s12, 8
	s_add_u32 s10, s56, s12
	s_addc_u32 s11, s57, 0
	v_mov_b32_e32 v4, 0x1000
	v_mov_b32_e32 v5, 1
	global_atomic_add v6, v4, v5, s[10:11] offset:1024 sc0
	s_waitcnt lgkmcnt(0)
	v_mul_lo_u32 v7, v2, 10
	s_waitcnt vmcnt(0)
	v_add_u32_e32 v6, 1, v6
	v_cmp_eq_u32_e32 vcc, v6, v7
	s_cbranch_vccz .Lgb_9_wait
	buffer_wbl2 sc1
	s_waitcnt vmcnt(0)
	v_mov_b32_e32 v4, 0x3000
	global_atomic_add v8, v4, v5, s[56:57] offset:1024 sc0
	v_mul_lo_u32 v7, v3, 10
	s_waitcnt vmcnt(0)
	v_add_u32_e32 v8, 1, v8
	v_cmp_eq_u32_e32 vcc, v8, v7
	s_cbranch_vccz .Lgb_9_wait
	v_mov_b32_e32 v9, 0x2400
	global_atomic_add v9, v5, s[56:57] offset:0
	global_atomic_add v9, v5, s[56:57] offset:256
	global_atomic_add v9, v5, s[56:57] offset:512
	global_atomic_add v9, v5, s[56:57] offset:768
	global_atomic_add v9, v5, s[56:57] offset:1024
	global_atomic_add v9, v5, s[56:57] offset:1280
	global_atomic_add v9, v5, s[56:57] offset:1536
	global_atomic_add v9, v5, s[56:57] offset:1792
	global_atomic_add v9, v5, s[56:57] offset:2048
	global_atomic_add v9, v5, s[56:57] offset:2304
	global_atomic_add v9, v5, s[56:57] offset:2560
	global_atomic_add v9, v5, s[56:57] offset:2816
	global_atomic_add v9, v5, s[56:57] offset:3072
	global_atomic_add v9, v5, s[56:57] offset:3328
	global_atomic_add v9, v5, s[56:57] offset:3584
	global_atomic_add v9, v5, s[56:57] offset:3840
	s_waitcnt vmcnt(0)
	s_branch .Lgb_9_done

.Lgb_9_spin:
	global_load_dword v8, v9, s[10:11] offset:1024 sc1
	s_waitcnt vmcnt(0)
	v_cmp_ne_u32_e32 vcc, 9, v8
	s_cbranch_vccnz .Lgb_9_done
	s_sleep 1
	s_add_u32 s12, s12, 1
	s_cmp_lt_u32 s12, 0x40000
	s_cbranch_scc1 .Lgb_9_spin
	s_branch .Lgb_9_done
.Lgb_9_sib:
	v_readlane_b32 s12, v249, 7
	s_mov_b64 exec, s[6:7]
	s_cmp_lg_u32 s12, 64
	s_cbranch_scc1 .Lgb_9_done
	buffer_inv sc1

.LBB0_1275:
	s_cmp_gt_i32 s59, 13
	s_cselect_b64 s[4:5], -1, 0
	s_and_b64 s[6:7], s[6:7], s[4:5]
	s_andn2_b64 vcc, exec, s[6:7]
	s_cbranch_vccnz .LBB0_1329
	s_waitcnt vmcnt(0) lgkmcnt(0)
	s_barrier
	s_mov_b64 s[6:7], exec
	v_readlane_b32 s8, v249, 5
	v_readlane_b32 s9, v249, 6
	v_readlane_b32 s12, v249, 4
	s_and_b64 s[8:9], s[6:7], s[8:9]
	s_mov_b64 exec, s[8:9]
	s_cbranch_execz .Lgb_10_sib
	v_mov_b32_e32 v1, 0x27e00
	ds_read2_b32 v[2:3], v1 offset1:1
	s_lshl_b32 s12, s12, 8
	s_add_u32 s10, s56, s12
	s_addc_u32 s11, s57, 0
	v_mov_b32_e32 v4, 0x1000
	v_mov_b32_e32 v5, 1
	global_atomic_add v6, v4, v5, s[10:11] offset:1024 sc0
	s_waitcnt lgkmcnt(0)
	v_mul_lo_u32 v7, v2, 11
	s_waitcnt vmcnt(0)
	v_add_u32_e32 v6, 1, v6
	v_cmp_eq_u32_e32 vcc, v6, v7
	s_cbranch_vccz .Lgb_10_wait
	buffer_wbl2 sc1
	s_waitcnt vmcnt(0)
	v_mov_b32_e32 v4, 0x3000
	global_atomic_add v8, v4, v5, s[56:57] offset:1024 sc0
	v_mul_lo_u32 v7, v3, 11
	s_waitcnt vmcnt(0)
	v_add_u32_e32 v8, 1, v8
	v_cmp_eq_u32_e32 vcc, v8, v7
	s_cbranch_vccz .Lgb_10_wait
	v_mov_b32_e32 v9, 0x2400
	global_atomic_add v9, v5, s[56:57] offset:0
	global_atomic_add v9, v5, s[56:57] offset:256
	global_atomic_add v9, v5, s[56:57] offset:512
	global_atomic_add v9, v5, s[56:57] offset:768
	global_atomic_add v9, v5, s[56:57] offset:1024
	global_atomic_add v9, v5, s[56:57] offset:1280
	global_atomic_add v9, v5, s[56:57] offset:1536
	global_atomic_add v9, v5, s[56:57] offset:1792
	global_atomic_add v9, v5, s[56:57] offset:2048
	global_atomic_add v9, v5, s[56:57] offset:2304
	global_atomic_add v9, v5, s[56:57] offset:2560
	global_atomic_add v9, v5, s[56:57] offset:2816
	global_atomic_add v9, v5, s[56:57] offset:3072
	global_atomic_add v9, v5, s[56:57] offset:3328
	global_atomic_add v9, v5, s[56:57] offset:3584
	global_atomic_add v9, v5, s[56:57] offset:3840
	s_waitcnt vmcnt(0)
	s_branch .Lgb_10_done

.Lgb_10_spin:
	global_load_dword v8, v9, s[10:11] offset:1024 sc1
	s_waitcnt vmcnt(0)
	v_cmp_ne_u32_e32 vcc, 10, v8
	s_cbranch_vccnz .Lgb_10_done
	s_sleep 1
	s_add_u32 s12, s12, 1
	s_cmp_lt_u32 s12, 0x40000
	s_cbranch_scc1 .Lgb_10_spin
	s_branch .Lgb_10_done

.LBB0_1346:
	s_cmp_lt_i32 s58, 14
	s_cselect_b64 s[2:3], -1, 0
	s_cmp_gt_i32 s59, 14
	s_cselect_b64 s[0:1], -1, 0
	s_and_b64 s[2:3], s[2:3], s[0:1]
	s_andn2_b64 vcc, exec, s[2:3]
	s_cbranch_vccnz .LBB0_1400
	s_waitcnt vmcnt(0) lgkmcnt(0)
	s_barrier
	s_mov_b64 s[2:3], exec
	v_readlane_b32 s4, v249, 5
	v_readlane_b32 s5, v249, 6
	v_readlane_b32 s8, v249, 4
	s_and_b64 s[4:5], s[2:3], s[4:5]
	s_mov_b64 exec, s[4:5]
	s_cbranch_execz .Lgb_11_sib
	v_mov_b32_e32 v1, 0x27e00
	ds_read2_b32 v[2:3], v1 offset1:1
	s_lshl_b32 s8, s8, 8
	s_add_u32 s6, s56, s8
	s_addc_u32 s7, s57, 0
	v_mov_b32_e32 v4, 0x1000
	v_mov_b32_e32 v5, 1
	global_atomic_add v6, v4, v5, s[6:7] offset:1024 sc0
	s_waitcnt lgkmcnt(0)
	v_mul_lo_u32 v7, v2, 12
	s_waitcnt vmcnt(0)
	v_add_u32_e32 v6, 1, v6
	v_cmp_eq_u32_e32 vcc, v6, v7
	s_cbranch_vccz .Lgb_11_wait
	buffer_wbl2 sc1
	s_waitcnt vmcnt(0)
	v_mov_b32_e32 v4, 0x3000
	global_atomic_add v8, v4, v5, s[56:57] offset:1024 sc0
	v_mul_lo_u32 v7, v3, 12
	s_waitcnt vmcnt(0)
	v_add_u32_e32 v8, 1, v8
	v_cmp_eq_u32_e32 vcc, v8, v7
	s_cbranch_vccz .Lgb_11_wait
	v_mov_b32_e32 v9, 0x2400
	global_atomic_add v9, v5, s[56:57] offset:0
	global_atomic_add v9, v5, s[56:57] offset:256
	global_atomic_add v9, v5, s[56:57] offset:512
	global_atomic_add v9, v5, s[56:57] offset:768
	global_atomic_add v9, v5, s[56:57] offset:1024
	global_atomic_add v9, v5, s[56:57] offset:1280
	global_atomic_add v9, v5, s[56:57] offset:1536
	global_atomic_add v9, v5, s[56:57] offset:1792
	global_atomic_add v9, v5, s[56:57] offset:2048
	global_atomic_add v9, v5, s[56:57] offset:2304
	global_atomic_add v9, v5, s[56:57] offset:2560
	global_atomic_add v9, v5, s[56:57] offset:2816
	global_atomic_add v9, v5, s[56:57] offset:3072
	global_atomic_add v9, v5, s[56:57] offset:3328
	global_atomic_add v9, v5, s[56:57] offset:3584
	global_atomic_add v9, v5, s[56:57] offset:3840
	s_waitcnt vmcnt(0)
	s_branch .Lgb_11_done

.Lgb_11_spin:
	global_load_dword v8, v9, s[6:7] offset:1024 sc1
	s_waitcnt vmcnt(0)
	v_cmp_ne_u32_e32 vcc, 11, v8
	s_cbranch_vccnz .Lgb_11_done
	s_sleep 1
	s_add_u32 s8, s8, 1
	s_cmp_lt_u32 s8, 0x40000
	s_cbranch_scc1 .Lgb_11_spin
	s_branch .Lgb_11_done
.Lgb_11_sib:
	v_readlane_b32 s8, v249, 7
	s_mov_b64 exec, s[2:3]
	s_cmp_lg_u32 s8, 64
	s_cbranch_scc1 .Lgb_11_done
	buffer_inv sc1

.LBB0_1555:
	s_cmp_gt_i32 s59, 16
	s_cselect_b64 s[4:5], -1, 0
	s_and_b64 s[0:1], s[10:11], s[4:5]
	s_andn2_b64 vcc, exec, s[0:1]
	s_cbranch_vccnz .LBB0_1609
	s_waitcnt vmcnt(0) lgkmcnt(0)
	s_barrier
	s_mov_b64 s[0:1], exec
	v_readlane_b32 s2, v249, 5
	v_readlane_b32 s3, v249, 6
	v_readlane_b32 s8, v249, 4
	s_and_b64 s[2:3], s[0:1], s[2:3]
	s_mov_b64 exec, s[2:3]
	s_cbranch_execz .Lgb_12_sib
	v_mov_b32_e32 v1, 0x27e00
	ds_read2_b32 v[2:3], v1 offset1:1
	s_lshl_b32 s8, s8, 8
	s_add_u32 s6, s56, s8
	s_addc_u32 s7, s57, 0
	v_mov_b32_e32 v4, 0x1000
	v_mov_b32_e32 v5, 1
	global_atomic_add v6, v4, v5, s[6:7] offset:1024 sc0
	s_waitcnt lgkmcnt(0)
	v_mul_lo_u32 v7, v2, 13
	s_waitcnt vmcnt(0)
	v_add_u32_e32 v6, 1, v6
	v_cmp_eq_u32_e32 vcc, v6, v7
	s_cbranch_vccz .Lgb_12_wait
	buffer_wbl2 sc1
	s_waitcnt vmcnt(0)
	v_mov_b32_e32 v4, 0x3000
	global_atomic_add v8, v4, v5, s[56:57] offset:1024 sc0
	v_mul_lo_u32 v7, v3, 13
	s_waitcnt vmcnt(0)
	v_add_u32_e32 v8, 1, v8
	v_cmp_eq_u32_e32 vcc, v8, v7
	s_cbranch_vccz .Lgb_12_wait
	v_mov_b32_e32 v9, 0x2400
	global_atomic_add v9, v5, s[56:57] offset:0
	global_atomic_add v9, v5, s[56:57] offset:256
	global_atomic_add v9, v5, s[56:57] offset:512
	global_atomic_add v9, v5, s[56:57] offset:768
	global_atomic_add v9, v5, s[56:57] offset:1024
	global_atomic_add v9, v5, s[56:57] offset:1280
	global_atomic_add v9, v5, s[56:57] offset:1536
	global_atomic_add v9, v5, s[56:57] offset:1792
	global_atomic_add v9, v5, s[56:57] offset:2048
	global_atomic_add v9, v5, s[56:57] offset:2304
	global_atomic_add v9, v5, s[56:57] offset:2560
	global_atomic_add v9, v5, s[56:57] offset:2816
	global_atomic_add v9, v5, s[56:57] offset:3072
	global_atomic_add v9, v5, s[56:57] offset:3328
	global_atomic_add v9, v5, s[56:57] offset:3584
	global_atomic_add v9, v5, s[56:57] offset:3840
	s_waitcnt vmcnt(0)
	s_branch .Lgb_12_done

.Lgb_12_spin:
	global_load_dword v8, v9, s[6:7] offset:1024 sc1
	s_waitcnt vmcnt(0)
	v_cmp_ne_u32_e32 vcc, 12, v8
	s_cbranch_vccnz .Lgb_12_done
	s_sleep 1
	s_add_u32 s8, s8, 1
	s_cmp_lt_u32 s8, 0x40000
	s_cbranch_scc1 .Lgb_12_spin
	s_branch .Lgb_12_done

.LBB0_1626:
	s_cmp_gt_i32 s59, 17
	s_cselect_b64 s[4:5], -1, 0
	s_and_b64 s[0:1], s[0:1], s[4:5]
	s_andn2_b64 vcc, exec, s[0:1]
	s_cbranch_vccnz .LBB0_1680
	s_waitcnt vmcnt(0) lgkmcnt(0)
	s_barrier
	s_mov_b64 s[0:1], exec
	v_readlane_b32 s2, v249, 5
	v_readlane_b32 s3, v249, 6
	v_readlane_b32 s8, v249, 4
	s_and_b64 s[2:3], s[0:1], s[2:3]
	s_mov_b64 exec, s[2:3]
	s_cbranch_execz .Lgb_13_sib
	v_mov_b32_e32 v1, 0x27e00
	ds_read2_b32 v[2:3], v1 offset1:1
	s_lshl_b32 s8, s8, 8
	s_add_u32 s6, s56, s8
	s_addc_u32 s7, s57, 0
	v_mov_b32_e32 v4, 0x1000
	v_mov_b32_e32 v5, 1
	global_atomic_add v6, v4, v5, s[6:7] offset:1024 sc0
	s_waitcnt lgkmcnt(0)
	v_mul_lo_u32 v7, v2, 14
	s_waitcnt vmcnt(0)
	v_add_u32_e32 v6, 1, v6
	v_cmp_eq_u32_e32 vcc, v6, v7
	s_cbranch_vccz .Lgb_13_wait
	buffer_wbl2 sc1
	s_waitcnt vmcnt(0)
	v_mov_b32_e32 v4, 0x3000
	global_atomic_add v8, v4, v5, s[56:57] offset:1024 sc0
	v_mul_lo_u32 v7, v3, 14
	s_waitcnt vmcnt(0)
	v_add_u32_e32 v8, 1, v8
	v_cmp_eq_u32_e32 vcc, v8, v7
	s_cbranch_vccz .Lgb_13_wait
	v_mov_b32_e32 v9, 0x2400
	global_atomic_add v9, v5, s[56:57] offset:0
	global_atomic_add v9, v5, s[56:57] offset:256
	global_atomic_add v9, v5, s[56:57] offset:512
	global_atomic_add v9, v5, s[56:57] offset:768
	global_atomic_add v9, v5, s[56:57] offset:1024
	global_atomic_add v9, v5, s[56:57] offset:1280
	global_atomic_add v9, v5, s[56:57] offset:1536
	global_atomic_add v9, v5, s[56:57] offset:1792
	global_atomic_add v9, v5, s[56:57] offset:2048
	global_atomic_add v9, v5, s[56:57] offset:2304
	global_atomic_add v9, v5, s[56:57] offset:2560
	global_atomic_add v9, v5, s[56:57] offset:2816
	global_atomic_add v9, v5, s[56:57] offset:3072
	global_atomic_add v9, v5, s[56:57] offset:3328
	global_atomic_add v9, v5, s[56:57] offset:3584
	global_atomic_add v9, v5, s[56:57] offset:3840
	s_waitcnt vmcnt(0)
	s_branch .Lgb_13_done

.Lgb_13_spin:
	global_load_dword v8, v9, s[6:7] offset:1024 sc1
	s_waitcnt vmcnt(0)
	v_cmp_ne_u32_e32 vcc, 13, v8
	s_cbranch_vccnz .Lgb_13_done
	s_sleep 1
	s_add_u32 s8, s8, 1
	s_cmp_lt_u32 s8, 0x40000
	s_cbranch_scc1 .Lgb_13_spin
	s_branch .Lgb_13_done
